# in-proj: units 1..4 of each workgroup visited in an order rotated by its column group, so tile types (rope/plain/gate epilogues) differ across workgroups in a round
# speedup vs baseline: 1.0092x; 1.0092x over previous
.LBB0_105:
	s_add_i32 s66, s66, 1
	s_mul_i32 s6, s66, s81
	s_mul_hi_u32 s7, s66, s33
	s_add_i32 s7, s7, s6
	s_mul_i32 s6, s66, s33
	s_add_u32 s6, s6, s2
	s_addc_u32 s7, s7, s3
	v_mov_b64_e32 v[0:1], 0x500
	v_cmp_lt_i64_e64 s[38:39], s[6:7], v[0:1]
	v_mov_b64_e32 v[0:1], 0x4ff
	v_cmp_gt_i64_e32 vcc, s[6:7], v[0:1]
	s_cbranch_vccnz .LBB0_107
	s_cmp_eq_u32 s33, 0x100
	s_cbranch_scc0 .Lnorot
	s_lshr_b32 s7, s6, 8
	s_and_b32 s36, s6, 0xff
	s_lshr_b32 s37, s36, 6
	s_add_u32 s7, s7, s37
	s_sub_u32 s7, s7, 1
	s_and_b32 s7, s7, 3
	s_add_u32 s7, s7, 1
	s_lshl_b32 s7, s7, 8
	s_or_b32 s6, s7, s36
.Lnorot:
	s_ashr_i32 s7, s6, 31
	s_lshr_b32 s7, s7, 29
	s_add_i32 s7, s6, s7
	s_ashr_i32 s36, s7, 3
	s_and_b32 s7, s7, -8
	s_sub_i32 s6, s6, s7
	s_cmp_lt_i32 s6, 0
	s_cselect_b32 s7, s72, 0xa0
	s_mul_i32 s6, s6, s7
	s_add_i32 s6, s6, s36
	s_mul_hi_i32 s7, s6, 0x66666667
	s_lshr_b32 s36, s7, 31
	s_ashr_i32 s7, s7, 6
	s_add_i32 s7, s7, s36
	s_lshl_b32 s37, s7, 3
	s_sub_i32 s36, 64, s37
	s_min_i32 s40, s36, 8
	s_abs_i32 s36, s40
	v_cvt_f32_u32_e32 v0, s36
	s_sub_i32 s42, 0, s36
	s_mulk_i32 s7, 0xa0
	s_sub_i32 s6, s6, s7
	v_rcp_iflag_f32_e32 v0, v0
	s_abs_i32 s7, s6
	s_xor_b32 s41, s6, s40
	s_ashr_i32 s41, s41, 31
	v_mul_f32_e32 v0, 0x4f7ffffe, v0
	v_cvt_u32_f32_e32 v0, v0
	s_nop 0
	v_readfirstlane_b32 s43, v0
	s_mul_i32 s42, s42, s43
	s_mul_hi_u32 s42, s43, s42
	s_add_i32 s43, s43, s42
	s_mul_hi_u32 s42, s7, s43
	s_mul_i32 s43, s42, s36
	s_sub_i32 s7, s7, s43
	s_add_i32 s46, s42, 1
	s_sub_i32 s43, s7, s36
	s_cmp_ge_u32 s7, s36
	s_cselect_b32 s42, s46, s42
	s_cselect_b32 s7, s43, s7
	s_add_i32 s43, s42, 1
	s_cmp_ge_u32 s7, s36
	s_cselect_b32 s7, s43, s42
	s_xor_b32 s7, s7, s41
	s_sub_i32 s36, s7, s41
	s_mul_i32 s7, s36, s40
	s_sub_i32 s6, s6, s7
	s_add_i32 s94, s37, s6
